# v10 + QKVZ GEMM epilogue: plain (no rope-table loads, no packed rope/scale math, no selects) copy for tiles with all columns >= 1280
# baseline (speedup 1.0000x reference)
; #define LAS __attribute__((address_space(3)))
; __device__ __forceinline__ unsigned pk2(float lo, float hi) { f32x2 v = {lo, hi}; nbf2 r = __builtin_convertvector(v, nbf2); return __builtin_bit_cast(unsigned, r); }
;     __device__ __forceinline__ void operator()(f32x4 (&acc)[2][2][4][2], const pg8::Unit& u, int wr, int wc, int fr, int fq, LAS unsigned char* lds) const {
;         const float qs = 0.125f * LOG2E;
; #pragma unroll
;         for (int ai = 0; ai < 2; ++ai)
; #pragma unroll
;             for (int m = 0; m < 4; ++m) {
;                 const int r = u.pm * 256 + ai * 128 + wr * 64 + m * 16 + fr;
;                 const bool lat = r < NLAT;
;                 const int t = r & (SEQ - 1);
;                 const int val = (wc & 1) ? (t & 63) : (t >> 6);
;                 const f32x4 cs = *(const f32x4*)(rope + val * 32 + 4 * fq), sn = *(const f32x4*)(rope + val * 32 + 16 + 4 * fq);
;                 bf16_t* rowp = O + (size_t)r * NQKVZ;
; #pragma unroll
;                 for (int bj = 0; bj < 2; ++bj) {
;                     const int cb = u.pn * 256 + bj * 128 + wc * 32;
;                     f32x4 t1 = acc[ai][bj][m][0], t2 = acc[ai][bj][m][1];
;                     if (cb < 1280 && lat) { const f32x4 o1 = t1 * cs - t2 * sn, o2 = t2 * cs + t1 * sn; t1 = o1; t2 = o2; }
;                     if (cb < 1024) { t1 = t1 * qs; t2 = t2 * qs; }
;                     u32x4 w; w.x = pk2(t1[0], t1[1]); w.y = pk2(t1[2], t1[3]); w.z = pk2(t2[0], t2[1]); w.w = pk2(t2[2], t2[3]);
;                     *(u32x4*)(rowp + cb + 8 * fq) = w;
;                 }
;             }
.LBB0_188:
	s_lshl_b32 s96, s1, 8
	s_or_b32 s96, s96, s83
	s_cmpk_ge_i32 s96, 0x500
	s_cbranch_scc1 .Lqkvz_plain
	s_lshl_b32 s55, s0, 8
	s_add_i32 s55, s55, s82
	s_bfe_u32 s0, s55, 0x60006
	v_mov_b32_e32 v158, s0
	v_cndmask_b32_e64 v136, v150, v158, s[2:3]
	v_lshlrev_b32_e32 v136, 7, v136
	v_lshl_add_u64 v[164:165], v[140:141], 0, v[136:137]
	global_load_dwordx4 v[160:163], v[164:165], off offset:64
	s_nop 0
	global_load_dwordx4 v[164:167], v[164:165], off
	s_lshl_b32 s0, s1, 8
	s_or_b32 s8, s0, s83
	v_or_b32_e32 v136, s55, v150
	s_cmpk_lt_i32 s8, 0x500
	v_cmp_gt_i32_e32 vcc, s81, v136
	v_mad_i64_i32 v[168:169], s[0:1], v136, s90, v[138:139]
	s_cselect_b64 s[64:65], -1, 0
	s_and_b64 s[0:1], s[64:65], vcc
	s_cmpk_lt_i32 s8, 0x400
	s_cselect_b64 s[6:7], -1, 0
	s_ashr_i32 s9, s8, 31
	s_lshl_b64 s[70:71], s[8:9], 1
	v_cndmask_b32_e64 v136, v152, v158, s[2:3]
	v_lshlrev_b32_e32 v136, 7, v136
	v_lshl_add_u64 v[170:171], v[140:141], 0, v[136:137]
	s_waitcnt vmcnt(0)
	v_pk_mul_f32 v[172:173], v[122:123], v[162:163]
	v_pk_mul_f32 v[174:175], v[120:121], v[160:161]
	v_pk_mul_f32 v[176:177], v[126:127], v[162:163]
	v_pk_mul_f32 v[178:179], v[124:125], v[160:161]
	v_pk_fma_f32 v[172:173], v[126:127], v[166:167], v[172:173] neg_lo:[0,0,1] neg_hi:[0,0,1]
	v_pk_fma_f32 v[174:175], v[124:125], v[164:165], v[174:175] neg_lo:[0,0,1] neg_hi:[0,0,1]
	v_pk_fma_f32 v[176:177], v[122:123], v[166:167], v[176:177]
	v_pk_fma_f32 v[178:179], v[120:121], v[164:165], v[178:179]
	v_cndmask_b32_e64 v127, v127, v173, s[0:1]
	v_cndmask_b32_e64 v126, v126, v172, s[0:1]
	v_cndmask_b32_e64 v125, v125, v175, s[0:1]
	v_cndmask_b32_e64 v124, v124, v174, s[0:1]
	v_cndmask_b32_e64 v123, v123, v177, s[0:1]
	v_cndmask_b32_e64 v122, v122, v176, s[0:1]
	v_cndmask_b32_e64 v121, v121, v179, s[0:1]
	v_cndmask_b32_e64 v120, v120, v178, s[0:1]
	s_or_b32 s0, s8, 0x80
	v_pk_mul_f32 v[180:181], v[114:115], v[162:163]
	v_pk_mul_f32 v[182:183], v[112:113], v[160:161]
	v_pk_mul_f32 v[162:163], v[118:119], v[162:163]
	v_pk_mul_f32 v[160:161], v[116:117], v[160:161]
	s_cmpk_lt_i32 s0, 0x500
	v_pk_fma_f32 v[180:181], v[118:119], v[166:167], v[180:181] neg_lo:[0,0,1] neg_hi:[0,0,1]
	v_pk_fma_f32 v[182:183], v[116:117], v[164:165], v[182:183] neg_lo:[0,0,1] neg_hi:[0,0,1]
	v_pk_fma_f32 v[162:163], v[114:115], v[166:167], v[162:163]
	v_pk_fma_f32 v[160:161], v[112:113], v[164:165], v[160:161]
	v_pk_mul_f32 v[164:165], v[126:127], s[50:51] op_sel_hi:[1,0]
	v_pk_mul_f32 v[166:167], v[124:125], s[50:51] op_sel_hi:[1,0]
	v_pk_mul_f32 v[172:173], v[120:121], s[50:51] op_sel_hi:[1,0]
	v_pk_mul_f32 v[174:175], v[122:123], s[50:51] op_sel_hi:[1,0]
	s_cselect_b64 s[66:67], -1, 0
	v_cndmask_b32_e64 v127, v127, v165, s[6:7]
	v_cndmask_b32_e64 v126, v126, v164, s[6:7]
	v_cndmask_b32_e64 v125, v125, v167, s[6:7]
	v_cndmask_b32_e64 v124, v124, v166, s[6:7]
	v_cndmask_b32_e64 v123, v123, v175, s[6:7]
	v_cndmask_b32_e64 v136, v122, v174, s[6:7]
	v_cndmask_b32_e64 v122, v121, v173, s[6:7]
	v_cndmask_b32_e64 v159, v120, v172, s[6:7]
	s_and_b64 vcc, s[66:67], vcc
	v_cvt_pk_bf16_f32 v120, v124, v125
	v_cvt_pk_bf16_f32 v121, v126, v127
	v_cvt_pk_bf16_f32 v122, v159, v122
	v_cvt_pk_bf16_f32 v123, v136, v123
	v_lshl_add_u64 v[124:125], v[168:169], 0, s[70:71]
	v_cndmask_b32_e32 v119, v119, v181, vcc
	v_cndmask_b32_e32 v118, v118, v180, vcc
	v_cndmask_b32_e32 v117, v117, v183, vcc
	v_cndmask_b32_e32 v116, v116, v182, vcc
	v_cndmask_b32_e32 v115, v115, v163, vcc
	v_cndmask_b32_e32 v114, v114, v162, vcc
	v_cndmask_b32_e32 v113, v113, v161, vcc
	v_cndmask_b32_e32 v112, v112, v160, vcc
	s_cmpk_lt_i32 s0, 0x400
	global_store_dwordx4 v[124:125], v[120:123], off
	v_pk_mul_f32 v[126:127], v[112:113], s[50:51] op_sel_hi:[1,0]
	v_pk_mul_f32 v[160:161], v[114:115], s[50:51] op_sel_hi:[1,0]
	v_pk_mul_f32 v[120:121], v[116:117], s[50:51] op_sel_hi:[1,0]
	v_pk_mul_f32 v[122:123], v[118:119], s[50:51] op_sel_hi:[1,0]
	s_cselect_b64 s[8:9], -1, 0
	v_cndmask_b32_e64 v119, v119, v123, s[8:9]
	v_cndmask_b32_e64 v118, v118, v122, s[8:9]
	v_cndmask_b32_e64 v117, v117, v121, s[8:9]
	v_cndmask_b32_e64 v116, v116, v120, s[8:9]
	v_cndmask_b32_e64 v115, v115, v161, s[8:9]
	v_cndmask_b32_e64 v120, v114, v160, s[8:9]
	v_cndmask_b32_e64 v114, v113, v127, s[8:9]
	v_cndmask_b32_e64 v121, v112, v126, s[8:9]
	v_cvt_pk_bf16_f32 v112, v116, v117
	v_cvt_pk_bf16_f32 v113, v118, v119
	v_cvt_pk_bf16_f32 v114, v121, v114
	v_cvt_pk_bf16_f32 v115, v120, v115
	global_store_dwordx4 v[124:125], v[112:115], off offset:256
	global_load_dwordx4 v[112:115], v[170:171], off offset:64
	s_nop 0
	global_load_dwordx4 v[116:119], v[170:171], off
	v_or_b32_e32 v120, s55, v152
	v_cmp_gt_i32_e32 vcc, s81, v120
	v_mad_i64_i32 v[120:121], s[0:1], v120, s90, v[138:139]
	s_and_b64 s[0:1], s[64:65], vcc
	s_and_b64 vcc, s[66:67], vcc
	v_cndmask_b32_e64 v122, v153, v158, s[2:3]
	v_lshlrev_b32_e32 v136, 7, v122
	v_lshl_add_u64 v[120:121], v[120:121], 0, s[70:71]
	v_lshl_add_u64 v[122:123], v[140:141], 0, v[136:137]
	s_waitcnt vmcnt(1)
	v_pk_mul_f32 v[124:125], v[106:107], v[114:115]
	v_pk_mul_f32 v[126:127], v[104:105], v[112:113]
	v_pk_mul_f32 v[160:161], v[110:111], v[114:115]
	v_pk_mul_f32 v[162:163], v[108:109], v[112:113]
	v_pk_mul_f32 v[164:165], v[98:99], v[114:115]
	v_pk_mul_f32 v[166:167], v[96:97], v[112:113]
	v_pk_mul_f32 v[114:115], v[102:103], v[114:115]
	v_pk_mul_f32 v[112:113], v[100:101], v[112:113]
	s_waitcnt vmcnt(0)
; __device__ __forceinline__ unsigned pk2(float lo, float hi) { f32x2 v = {lo, hi}; nbf2 r = __builtin_convertvector(v, nbf2); return __builtin_bit_cast(unsigned, r); }
;     __device__ __forceinline__ void operator()(f32x4 (&acc)[2][2][4][2], const pg8::Unit& u, int wr, int wc, int fr, int fq, LAS unsigned char* lds) const {
;     ...
;             for (int m = 0; m < 4; ++m) {
;                 const int r = u.pm * 256 + ai * 128 + wr * 64 + m * 16 + fr;
;                 const bool lat = r < NLAT;
;                 const int t = r & (SEQ - 1);
;                 const int val = (wc & 1) ? (t & 63) : (t >> 6);
;                 const f32x4 cs = *(const f32x4*)(rope + val * 32 + 4 * fq), sn = *(const f32x4*)(rope + val * 32 + 16 + 4 * fq);
;                 bf16_t* rowp = O + (size_t)r * NQKVZ;
; #pragma unroll
;                 for (int bj = 0; bj < 2; ++bj) {
;                     const int cb = u.pn * 256 + bj * 128 + wc * 32;
;                     f32x4 t1 = acc[ai][bj][m][0], t2 = acc[ai][bj][m][1];
;                     if (cb < 1280 && lat) { const f32x4 o1 = t1 * cs - t2 * sn, o2 = t2 * cs + t1 * sn; t1 = o1; t2 = o2; }
;                     if (cb < 1024) { t1 = t1 * qs; t2 = t2 * qs; }
;                     u32x4 w; w.x = pk2(t1[0], t1[1]); w.y = pk2(t1[2], t1[3]); w.z = pk2(t2[0], t2[1]); w.w = pk2(t2[2], t2[3]);
;                     *(u32x4*)(rowp + cb + 8 * fq) = w;
;                 }
	v_pk_fma_f32 v[124:125], v[110:111], v[118:119], v[124:125] neg_lo:[0,0,1] neg_hi:[0,0,1]
	v_pk_fma_f32 v[126:127], v[108:109], v[116:117], v[126:127] neg_lo:[0,0,1] neg_hi:[0,0,1]
	v_pk_fma_f32 v[160:161], v[106:107], v[118:119], v[160:161]
	v_pk_fma_f32 v[162:163], v[104:105], v[116:117], v[162:163]
	v_pk_fma_f32 v[164:165], v[102:103], v[118:119], v[164:165] neg_lo:[0,0,1] neg_hi:[0,0,1]
	v_pk_fma_f32 v[166:167], v[100:101], v[116:117], v[166:167] neg_lo:[0,0,1] neg_hi:[0,0,1]
	v_pk_fma_f32 v[114:115], v[98:99], v[118:119], v[114:115]
	v_pk_fma_f32 v[112:113], v[96:97], v[116:117], v[112:113]
	v_cndmask_b32_e64 v111, v111, v125, s[0:1]
	v_cndmask_b32_e64 v110, v110, v124, s[0:1]
	v_cndmask_b32_e64 v109, v109, v127, s[0:1]
	v_cndmask_b32_e64 v108, v108, v126, s[0:1]
	v_cndmask_b32_e64 v107, v107, v161, s[0:1]
	v_cndmask_b32_e64 v106, v106, v160, s[0:1]
	v_cndmask_b32_e64 v105, v105, v163, s[0:1]
	v_cndmask_b32_e64 v104, v104, v162, s[0:1]
	v_cndmask_b32_e32 v103, v103, v165, vcc
	v_cndmask_b32_e32 v102, v102, v164, vcc
	v_cndmask_b32_e32 v101, v101, v167, vcc
	v_cndmask_b32_e32 v100, v100, v166, vcc
	v_cndmask_b32_e32 v99, v99, v115, vcc
	v_cndmask_b32_e32 v98, v98, v114, vcc
	v_cndmask_b32_e32 v97, v97, v113, vcc
	v_cndmask_b32_e32 v96, v96, v112, vcc
	v_pk_mul_f32 v[112:113], v[108:109], s[50:51] op_sel_hi:[1,0]
	v_pk_mul_f32 v[114:115], v[110:111], s[50:51] op_sel_hi:[1,0]
	v_pk_mul_f32 v[116:117], v[104:105], s[50:51] op_sel_hi:[1,0]
	v_pk_mul_f32 v[118:119], v[106:107], s[50:51] op_sel_hi:[1,0]
	v_pk_mul_f32 v[124:125], v[100:101], s[50:51] op_sel_hi:[1,0]
	v_pk_mul_f32 v[126:127], v[102:103], s[50:51] op_sel_hi:[1,0]
	v_pk_mul_f32 v[160:161], v[96:97], s[50:51] op_sel_hi:[1,0]
	v_pk_mul_f32 v[162:163], v[98:99], s[50:51] op_sel_hi:[1,0]
	v_cndmask_b32_e64 v111, v111, v115, s[6:7]
	v_cndmask_b32_e64 v110, v110, v114, s[6:7]
	v_cndmask_b32_e64 v109, v109, v113, s[6:7]
	v_cndmask_b32_e64 v108, v108, v112, s[6:7]
	v_cndmask_b32_e64 v107, v107, v119, s[6:7]
	v_cndmask_b32_e64 v106, v106, v118, s[6:7]
	v_cndmask_b32_e64 v105, v105, v117, s[6:7]
	v_cndmask_b32_e64 v104, v104, v116, s[6:7]
	v_cndmask_b32_e64 v103, v103, v127, s[8:9]
	v_cndmask_b32_e64 v102, v102, v126, s[8:9]
	v_cndmask_b32_e64 v101, v101, v125, s[8:9]
	v_cndmask_b32_e64 v100, v100, v124, s[8:9]
	v_cndmask_b32_e64 v112, v99, v163, s[8:9]
	v_cndmask_b32_e64 v113, v98, v162, s[8:9]
	v_cndmask_b32_e64 v114, v97, v161, s[8:9]
	v_cndmask_b32_e64 v115, v96, v160, s[8:9]
	v_cvt_pk_bf16_f32 v96, v108, v109
	v_cvt_pk_bf16_f32 v97, v110, v111
	v_cvt_pk_bf16_f32 v98, v104, v105
	v_cvt_pk_bf16_f32 v99, v106, v107
	v_cvt_pk_bf16_f32 v100, v100, v101
	v_cvt_pk_bf16_f32 v101, v102, v103
	v_cvt_pk_bf16_f32 v102, v115, v114
	v_cvt_pk_bf16_f32 v103, v113, v112
	global_store_dwordx4 v[120:121], v[96:99], off
	global_store_dwordx4 v[120:121], v[100:103], off offset:256
	global_load_dwordx4 v[96:99], v[122:123], off offset:64
	s_nop 0
	global_load_dwordx4 v[100:103], v[122:123], off
	v_or_b32_e32 v104, s55, v153
	v_cmp_gt_i32_e32 vcc, s81, v104
	v_mad_i64_i32 v[104:105], s[0:1], v104, s90, v[138:139]
	s_and_b64 s[0:1], s[64:65], vcc
	s_and_b64 vcc, s[66:67], vcc
	v_cndmask_b32_e64 v106, v154, v158, s[2:3]
	v_lshlrev_b32_e32 v136, 7, v106
	v_lshl_add_u64 v[104:105], v[104:105], 0, s[70:71]
	v_lshl_add_u64 v[106:107], v[140:141], 0, v[136:137]
	s_waitcnt vmcnt(1)
	v_pk_mul_f32 v[108:109], v[90:91], v[98:99]
	v_pk_mul_f32 v[110:111], v[88:89], v[96:97]
	v_pk_mul_f32 v[112:113], v[94:95], v[98:99]
	v_pk_mul_f32 v[114:115], v[92:93], v[96:97]
	v_pk_mul_f32 v[116:117], v[82:83], v[98:99]
	v_pk_mul_f32 v[118:119], v[80:81], v[96:97]
	v_pk_mul_f32 v[98:99], v[86:87], v[98:99]
	v_pk_mul_f32 v[96:97], v[84:85], v[96:97]
	s_waitcnt vmcnt(0)
	v_pk_fma_f32 v[108:109], v[94:95], v[102:103], v[108:109] neg_lo:[0,0,1] neg_hi:[0,0,1]
	v_pk_fma_f32 v[110:111], v[92:93], v[100:101], v[110:111] neg_lo:[0,0,1] neg_hi:[0,0,1]
	v_pk_fma_f32 v[112:113], v[90:91], v[102:103], v[112:113]
	v_pk_fma_f32 v[114:115], v[88:89], v[100:101], v[114:115]
	v_pk_fma_f32 v[116:117], v[86:87], v[102:103], v[116:117] neg_lo:[0,0,1] neg_hi:[0,0,1]
	v_pk_fma_f32 v[118:119], v[84:85], v[100:101], v[118:119] neg_lo:[0,0,1] neg_hi:[0,0,1]
	v_pk_fma_f32 v[98:99], v[82:83], v[102:103], v[98:99]
	v_pk_fma_f32 v[96:97], v[80:81], v[100:101], v[96:97]
	v_cndmask_b32_e64 v95, v95, v109, s[0:1]
	v_cndmask_b32_e64 v94, v94, v108, s[0:1]
	v_cndmask_b32_e64 v93, v93, v111, s[0:1]
	v_cndmask_b32_e64 v92, v92, v110, s[0:1]
	v_cndmask_b32_e64 v91, v91, v113, s[0:1]
	v_cndmask_b32_e64 v90, v90, v112, s[0:1]
	v_cndmask_b32_e64 v89, v89, v115, s[0:1]
	v_cndmask_b32_e64 v88, v88, v114, s[0:1]
	v_cndmask_b32_e32 v87, v87, v117, vcc
	v_cndmask_b32_e32 v86, v86, v116, vcc
	v_cndmask_b32_e32 v85, v85, v119, vcc
	v_cndmask_b32_e32 v84, v84, v118, vcc
	v_cndmask_b32_e32 v83, v83, v99, vcc
	v_cndmask_b32_e32 v82, v82, v98, vcc
	v_cndmask_b32_e32 v81, v81, v97, vcc
	v_cndmask_b32_e32 v80, v80, v96, vcc
	v_pk_mul_f32 v[96:97], v[92:93], s[50:51] op_sel_hi:[1,0]
	v_pk_mul_f32 v[98:99], v[94:95], s[50:51] op_sel_hi:[1,0]
	v_pk_mul_f32 v[100:101], v[88:89], s[50:51] op_sel_hi:[1,0]
	v_pk_mul_f32 v[102:103], v[90:91], s[50:51] op_sel_hi:[1,0]
	v_pk_mul_f32 v[108:109], v[84:85], s[50:51] op_sel_hi:[1,0]
	v_pk_mul_f32 v[110:111], v[86:87], s[50:51] op_sel_hi:[1,0]
	v_pk_mul_f32 v[112:113], v[80:81], s[50:51] op_sel_hi:[1,0]
	v_pk_mul_f32 v[114:115], v[82:83], s[50:51] op_sel_hi:[1,0]
	v_cndmask_b32_e64 v95, v95, v99, s[6:7]
	v_cndmask_b32_e64 v94, v94, v98, s[6:7]
	v_cndmask_b32_e64 v93, v93, v97, s[6:7]
	v_cndmask_b32_e64 v92, v92, v96, s[6:7]
; __device__ __forceinline__ unsigned pk2(float lo, float hi) { f32x2 v = {lo, hi}; nbf2 r = __builtin_convertvector(v, nbf2); return __builtin_bit_cast(unsigned, r); }
;     __device__ __forceinline__ void operator()(f32x4 (&acc)[2][2][4][2], const pg8::Unit& u, int wr, int wc, int fr, int fq, LAS unsigned char* lds) const {
;     ...
;             for (int m = 0; m < 4; ++m) {
;                 const int r = u.pm * 256 + ai * 128 + wr * 64 + m * 16 + fr;
;                 const bool lat = r < NLAT;
;                 const int t = r & (SEQ - 1);
;                 const int val = (wc & 1) ? (t & 63) : (t >> 6);
;                 const f32x4 cs = *(const f32x4*)(rope + val * 32 + 4 * fq), sn = *(const f32x4*)(rope + val * 32 + 16 + 4 * fq);
;                 bf16_t* rowp = O + (size_t)r * NQKVZ;
; #pragma unroll
;                 for (int bj = 0; bj < 2; ++bj) {
;                     const int cb = u.pn * 256 + bj * 128 + wc * 32;
;                     f32x4 t1 = acc[ai][bj][m][0], t2 = acc[ai][bj][m][1];
;                     if (cb < 1280 && lat) { const f32x4 o1 = t1 * cs - t2 * sn, o2 = t2 * cs + t1 * sn; t1 = o1; t2 = o2; }
;                     if (cb < 1024) { t1 = t1 * qs; t2 = t2 * qs; }
;                     u32x4 w; w.x = pk2(t1[0], t1[1]); w.y = pk2(t1[2], t1[3]); w.z = pk2(t2[0], t2[1]); w.w = pk2(t2[2], t2[3]);
;                     *(u32x4*)(rowp + cb + 8 * fq) = w;
;                 }
	v_cndmask_b32_e64 v91, v91, v103, s[6:7]
	v_cndmask_b32_e64 v90, v90, v102, s[6:7]
	v_cndmask_b32_e64 v89, v89, v101, s[6:7]
	v_cndmask_b32_e64 v88, v88, v100, s[6:7]
	v_cndmask_b32_e64 v87, v87, v111, s[8:9]
	v_cndmask_b32_e64 v86, v86, v110, s[8:9]
	v_cndmask_b32_e64 v85, v85, v109, s[8:9]
	v_cndmask_b32_e64 v84, v84, v108, s[8:9]
	v_cndmask_b32_e64 v96, v83, v115, s[8:9]
	v_cndmask_b32_e64 v97, v82, v114, s[8:9]
	v_cndmask_b32_e64 v98, v81, v113, s[8:9]
	v_cndmask_b32_e64 v99, v80, v112, s[8:9]
	v_cvt_pk_bf16_f32 v80, v92, v93
	v_cvt_pk_bf16_f32 v81, v94, v95
	v_cvt_pk_bf16_f32 v82, v88, v89
	v_cvt_pk_bf16_f32 v83, v90, v91
	v_cvt_pk_bf16_f32 v84, v84, v85
	v_cvt_pk_bf16_f32 v85, v86, v87
	v_cvt_pk_bf16_f32 v86, v99, v98
	v_cvt_pk_bf16_f32 v87, v97, v96
	global_store_dwordx4 v[104:105], v[80:83], off
	global_store_dwordx4 v[104:105], v[84:87], off offset:256
	global_load_dwordx4 v[82:85], v[106:107], off offset:64
	s_nop 0
	global_load_dwordx4 v[86:89], v[106:107], off
	v_or_b32_e32 v80, s55, v154
	v_cmp_gt_i32_e32 vcc, s81, v80
	v_mad_i64_i32 v[80:81], s[0:1], v80, s90, v[138:139]
	s_addk_i32 s55, 0x80
	s_bfe_u32 s0, s55, 0x60006
	v_lshl_add_u64 v[90:91], v[80:81], 0, s[70:71]
	v_mov_b32_e32 v80, s0
	s_and_b64 s[0:1], s[64:65], vcc
	s_and_b64 vcc, s[66:67], vcc
	v_cndmask_b32_e64 v81, v150, v80, s[2:3]
	v_lshlrev_b32_e32 v136, 7, v81
	v_lshl_add_u64 v[92:93], v[140:141], 0, v[136:137]
	s_waitcnt vmcnt(1)
	v_pk_mul_f32 v[94:95], v[74:75], v[84:85]
	v_pk_mul_f32 v[96:97], v[72:73], v[82:83]
	v_pk_mul_f32 v[98:99], v[78:79], v[84:85]
	v_pk_mul_f32 v[100:101], v[76:77], v[82:83]
	v_pk_mul_f32 v[102:103], v[66:67], v[84:85]
	v_pk_mul_f32 v[104:105], v[64:65], v[82:83]
	v_pk_mul_f32 v[84:85], v[70:71], v[84:85]
	v_pk_mul_f32 v[82:83], v[68:69], v[82:83]
	s_waitcnt vmcnt(0)
	v_pk_fma_f32 v[94:95], v[78:79], v[88:89], v[94:95] neg_lo:[0,0,1] neg_hi:[0,0,1]
	v_pk_fma_f32 v[96:97], v[76:77], v[86:87], v[96:97] neg_lo:[0,0,1] neg_hi:[0,0,1]
	v_pk_fma_f32 v[98:99], v[74:75], v[88:89], v[98:99]
	v_pk_fma_f32 v[100:101], v[72:73], v[86:87], v[100:101]
	v_pk_fma_f32 v[102:103], v[70:71], v[88:89], v[102:103] neg_lo:[0,0,1] neg_hi:[0,0,1]
	v_pk_fma_f32 v[104:105], v[68:69], v[86:87], v[104:105] neg_lo:[0,0,1] neg_hi:[0,0,1]
	v_pk_fma_f32 v[84:85], v[66:67], v[88:89], v[84:85]
	v_pk_fma_f32 v[82:83], v[64:65], v[86:87], v[82:83]
	v_cndmask_b32_e64 v79, v79, v95, s[0:1]
	v_cndmask_b32_e64 v78, v78, v94, s[0:1]
	v_cndmask_b32_e64 v77, v77, v97, s[0:1]
	v_cndmask_b32_e64 v76, v76, v96, s[0:1]
	v_cndmask_b32_e64 v75, v75, v99, s[0:1]
	v_cndmask_b32_e64 v74, v74, v98, s[0:1]
	v_cndmask_b32_e64 v73, v73, v101, s[0:1]
	v_cndmask_b32_e64 v72, v72, v100, s[0:1]
	v_cndmask_b32_e32 v71, v71, v103, vcc
	v_cndmask_b32_e32 v70, v70, v102, vcc
	v_cndmask_b32_e32 v69, v69, v105, vcc
	v_cndmask_b32_e32 v68, v68, v104, vcc
	v_cndmask_b32_e32 v67, v67, v85, vcc
	v_cndmask_b32_e32 v66, v66, v84, vcc
	v_cndmask_b32_e32 v65, v65, v83, vcc
	v_cndmask_b32_e32 v64, v64, v82, vcc
	v_pk_mul_f32 v[82:83], v[76:77], s[50:51] op_sel_hi:[1,0]
	v_pk_mul_f32 v[84:85], v[78:79], s[50:51] op_sel_hi:[1,0]
	v_pk_mul_f32 v[86:87], v[72:73], s[50:51] op_sel_hi:[1,0]
	v_pk_mul_f32 v[88:89], v[74:75], s[50:51] op_sel_hi:[1,0]
	v_pk_mul_f32 v[94:95], v[68:69], s[50:51] op_sel_hi:[1,0]
	v_pk_mul_f32 v[96:97], v[70:71], s[50:51] op_sel_hi:[1,0]
	v_pk_mul_f32 v[98:99], v[64:65], s[50:51] op_sel_hi:[1,0]
	v_pk_mul_f32 v[100:101], v[66:67], s[50:51] op_sel_hi:[1,0]
	v_cndmask_b32_e64 v79, v79, v85, s[6:7]
	v_cndmask_b32_e64 v78, v78, v84, s[6:7]
	v_cndmask_b32_e64 v77, v77, v83, s[6:7]
	v_cndmask_b32_e64 v76, v76, v82, s[6:7]
	v_cndmask_b32_e64 v75, v75, v89, s[6:7]
	v_cndmask_b32_e64 v74, v74, v88, s[6:7]
	v_cndmask_b32_e64 v73, v73, v87, s[6:7]
	v_cndmask_b32_e64 v72, v72, v86, s[6:7]
	v_cndmask_b32_e64 v71, v71, v97, s[8:9]
	v_cndmask_b32_e64 v70, v70, v96, s[8:9]
	v_cndmask_b32_e64 v69, v69, v95, s[8:9]
	v_cndmask_b32_e64 v68, v68, v94, s[8:9]
	v_cndmask_b32_e64 v81, v67, v101, s[8:9]
	v_cndmask_b32_e64 v82, v66, v100, s[8:9]
	v_cndmask_b32_e64 v83, v65, v99, s[8:9]
	v_cndmask_b32_e64 v84, v64, v98, s[8:9]
	v_cvt_pk_bf16_f32 v64, v76, v77
	v_cvt_pk_bf16_f32 v65, v78, v79
	v_cvt_pk_bf16_f32 v66, v72, v73
	v_cvt_pk_bf16_f32 v67, v74, v75
	v_cvt_pk_bf16_f32 v68, v68, v69
	v_cvt_pk_bf16_f32 v69, v70, v71
	v_cvt_pk_bf16_f32 v70, v84, v83
	v_cvt_pk_bf16_f32 v71, v82, v81
	global_store_dwordx4 v[90:91], v[64:67], off
	global_store_dwordx4 v[90:91], v[68:71], off offset:256
	global_load_dwordx4 v[64:67], v[92:93], off offset:64
	s_nop 0
	global_load_dwordx4 v[68:71], v[92:93], off
	v_or_b32_e32 v72, s55, v150
	v_cmp_gt_i32_e32 vcc, s81, v72
	v_mad_i64_i32 v[72:73], s[0:1], v72, s90, v[138:139]
	s_and_b64 s[0:1], s[64:65], vcc
	s_and_b64 vcc, s[66:67], vcc
	v_cndmask_b32_e64 v74, v152, v80, s[2:3]
	v_lshl_add_u64 v[72:73], v[72:73], 0, s[70:71]
	v_lshlrev_b32_e32 v136, 7, v74
	v_lshl_add_u64 v[74:75], v[140:141], 0, v[136:137]
	s_waitcnt vmcnt(1)
	v_pk_mul_f32 v[76:77], v[58:59], v[66:67]
	v_pk_mul_f32 v[78:79], v[56:57], v[64:65]
	v_pk_mul_f32 v[82:83], v[62:63], v[66:67]
	v_pk_mul_f32 v[84:85], v[60:61], v[64:65]
	v_pk_mul_f32 v[86:87], v[50:51], v[66:67]
	v_pk_mul_f32 v[88:89], v[48:49], v[64:65]
	v_pk_mul_f32 v[66:67], v[54:55], v[66:67]
	v_pk_mul_f32 v[64:65], v[52:53], v[64:65]
	s_waitcnt vmcnt(0)
; __device__ __forceinline__ unsigned pk2(float lo, float hi) { f32x2 v = {lo, hi}; nbf2 r = __builtin_convertvector(v, nbf2); return __builtin_bit_cast(unsigned, r); }
;     __device__ __forceinline__ void operator()(f32x4 (&acc)[2][2][4][2], const pg8::Unit& u, int wr, int wc, int fr, int fq, LAS unsigned char* lds) const {
;     ...
;             for (int m = 0; m < 4; ++m) {
;                 const int r = u.pm * 256 + ai * 128 + wr * 64 + m * 16 + fr;
;                 const bool lat = r < NLAT;
;                 const int t = r & (SEQ - 1);
;                 const int val = (wc & 1) ? (t & 63) : (t >> 6);
;                 const f32x4 cs = *(const f32x4*)(rope + val * 32 + 4 * fq), sn = *(const f32x4*)(rope + val * 32 + 16 + 4 * fq);
;                 bf16_t* rowp = O + (size_t)r * NQKVZ;
; #pragma unroll
;                 for (int bj = 0; bj < 2; ++bj) {
;                     const int cb = u.pn * 256 + bj * 128 + wc * 32;
;                     f32x4 t1 = acc[ai][bj][m][0], t2 = acc[ai][bj][m][1];
;                     if (cb < 1280 && lat) { const f32x4 o1 = t1 * cs - t2 * sn, o2 = t2 * cs + t1 * sn; t1 = o1; t2 = o2; }
;                     if (cb < 1024) { t1 = t1 * qs; t2 = t2 * qs; }
;                     u32x4 w; w.x = pk2(t1[0], t1[1]); w.y = pk2(t1[2], t1[3]); w.z = pk2(t2[0], t2[1]); w.w = pk2(t2[2], t2[3]);
;                     *(u32x4*)(rowp + cb + 8 * fq) = w;
;                 }
	v_pk_fma_f32 v[76:77], v[62:63], v[70:71], v[76:77] neg_lo:[0,0,1] neg_hi:[0,0,1]
	v_pk_fma_f32 v[78:79], v[60:61], v[68:69], v[78:79] neg_lo:[0,0,1] neg_hi:[0,0,1]
	v_pk_fma_f32 v[82:83], v[58:59], v[70:71], v[82:83]
	v_pk_fma_f32 v[84:85], v[56:57], v[68:69], v[84:85]
	v_pk_fma_f32 v[86:87], v[54:55], v[70:71], v[86:87] neg_lo:[0,0,1] neg_hi:[0,0,1]
	v_pk_fma_f32 v[88:89], v[52:53], v[68:69], v[88:89] neg_lo:[0,0,1] neg_hi:[0,0,1]
	v_pk_fma_f32 v[66:67], v[50:51], v[70:71], v[66:67]
	v_pk_fma_f32 v[64:65], v[48:49], v[68:69], v[64:65]
	v_cndmask_b32_e64 v63, v63, v77, s[0:1]
	v_cndmask_b32_e64 v62, v62, v76, s[0:1]
	v_cndmask_b32_e64 v61, v61, v79, s[0:1]
	v_cndmask_b32_e64 v60, v60, v78, s[0:1]
	v_cndmask_b32_e64 v59, v59, v83, s[0:1]
	v_cndmask_b32_e64 v58, v58, v82, s[0:1]
	v_cndmask_b32_e64 v57, v57, v85, s[0:1]
	v_cndmask_b32_e64 v56, v56, v84, s[0:1]
	v_cndmask_b32_e32 v55, v55, v87, vcc
	v_cndmask_b32_e32 v54, v54, v86, vcc
	v_cndmask_b32_e32 v53, v53, v89, vcc
	v_cndmask_b32_e32 v52, v52, v88, vcc
	v_cndmask_b32_e32 v51, v51, v67, vcc
	v_cndmask_b32_e32 v50, v50, v66, vcc
	v_cndmask_b32_e32 v49, v49, v65, vcc
	v_cndmask_b32_e32 v48, v48, v64, vcc
	v_pk_mul_f32 v[64:65], v[60:61], s[50:51] op_sel_hi:[1,0]
	v_pk_mul_f32 v[66:67], v[62:63], s[50:51] op_sel_hi:[1,0]
	v_pk_mul_f32 v[68:69], v[56:57], s[50:51] op_sel_hi:[1,0]
	v_pk_mul_f32 v[70:71], v[58:59], s[50:51] op_sel_hi:[1,0]
	v_pk_mul_f32 v[76:77], v[52:53], s[50:51] op_sel_hi:[1,0]
	v_pk_mul_f32 v[78:79], v[54:55], s[50:51] op_sel_hi:[1,0]
	v_pk_mul_f32 v[82:83], v[48:49], s[50:51] op_sel_hi:[1,0]
	v_pk_mul_f32 v[84:85], v[50:51], s[50:51] op_sel_hi:[1,0]
	v_cndmask_b32_e64 v63, v63, v67, s[6:7]
	v_cndmask_b32_e64 v62, v62, v66, s[6:7]
	v_cndmask_b32_e64 v61, v61, v65, s[6:7]
	v_cndmask_b32_e64 v60, v60, v64, s[6:7]
	v_cndmask_b32_e64 v59, v59, v71, s[6:7]
	v_cndmask_b32_e64 v58, v58, v70, s[6:7]
	v_cndmask_b32_e64 v57, v57, v69, s[6:7]
	v_cndmask_b32_e64 v56, v56, v68, s[6:7]
	v_cndmask_b32_e64 v55, v55, v79, s[8:9]
	v_cndmask_b32_e64 v54, v54, v78, s[8:9]
	v_cndmask_b32_e64 v53, v53, v77, s[8:9]
	v_cndmask_b32_e64 v52, v52, v76, s[8:9]
	v_cndmask_b32_e64 v64, v51, v85, s[8:9]
	v_cndmask_b32_e64 v65, v50, v84, s[8:9]
	v_cndmask_b32_e64 v66, v49, v83, s[8:9]
	v_cndmask_b32_e64 v67, v48, v82, s[8:9]
	v_cvt_pk_bf16_f32 v48, v60, v61
	v_cvt_pk_bf16_f32 v49, v62, v63
	v_cvt_pk_bf16_f32 v50, v56, v57
	v_cvt_pk_bf16_f32 v51, v58, v59
	v_cvt_pk_bf16_f32 v52, v52, v53
	v_cvt_pk_bf16_f32 v53, v54, v55
	v_cvt_pk_bf16_f32 v54, v67, v66
	v_cvt_pk_bf16_f32 v55, v65, v64
	global_store_dwordx4 v[72:73], v[48:51], off
	global_store_dwordx4 v[72:73], v[52:55], off offset:256
	global_load_dwordx4 v[48:51], v[74:75], off offset:64
	s_nop 0
	global_load_dwordx4 v[52:55], v[74:75], off
	v_or_b32_e32 v56, s55, v152
	v_cmp_gt_i32_e32 vcc, s81, v56
	v_mad_i64_i32 v[56:57], s[0:1], v56, s90, v[138:139]
	s_and_b64 s[0:1], s[64:65], vcc
	s_and_b64 vcc, s[66:67], vcc
	v_cndmask_b32_e64 v58, v153, v80, s[2:3]
	v_lshl_add_u64 v[56:57], v[56:57], 0, s[70:71]
	v_lshlrev_b32_e32 v136, 7, v58
	v_lshl_add_u64 v[58:59], v[140:141], 0, v[136:137]
	s_waitcnt vmcnt(1)
	v_pk_mul_f32 v[60:61], v[42:43], v[50:51]
	v_pk_mul_f32 v[62:63], v[40:41], v[48:49]
	v_pk_mul_f32 v[64:65], v[46:47], v[50:51]
	v_pk_mul_f32 v[66:67], v[44:45], v[48:49]
	v_pk_mul_f32 v[68:69], v[34:35], v[50:51]
	v_pk_mul_f32 v[70:71], v[32:33], v[48:49]
	v_pk_mul_f32 v[50:51], v[38:39], v[50:51]
	v_pk_mul_f32 v[48:49], v[36:37], v[48:49]
	s_waitcnt vmcnt(0)
	v_pk_fma_f32 v[60:61], v[46:47], v[54:55], v[60:61] neg_lo:[0,0,1] neg_hi:[0,0,1]
	v_pk_fma_f32 v[62:63], v[44:45], v[52:53], v[62:63] neg_lo:[0,0,1] neg_hi:[0,0,1]
	v_pk_fma_f32 v[64:65], v[42:43], v[54:55], v[64:65]
	v_pk_fma_f32 v[66:67], v[40:41], v[52:53], v[66:67]
	v_pk_fma_f32 v[68:69], v[38:39], v[54:55], v[68:69] neg_lo:[0,0,1] neg_hi:[0,0,1]
	v_pk_fma_f32 v[70:71], v[36:37], v[52:53], v[70:71] neg_lo:[0,0,1] neg_hi:[0,0,1]
	v_pk_fma_f32 v[50:51], v[34:35], v[54:55], v[50:51]
	v_pk_fma_f32 v[48:49], v[32:33], v[52:53], v[48:49]
	v_cndmask_b32_e64 v47, v47, v61, s[0:1]
	v_cndmask_b32_e64 v46, v46, v60, s[0:1]
	v_cndmask_b32_e64 v45, v45, v63, s[0:1]
	v_cndmask_b32_e64 v44, v44, v62, s[0:1]
	v_cndmask_b32_e64 v43, v43, v65, s[0:1]
	v_cndmask_b32_e64 v42, v42, v64, s[0:1]
	v_cndmask_b32_e64 v41, v41, v67, s[0:1]
	v_cndmask_b32_e64 v40, v40, v66, s[0:1]
	v_cndmask_b32_e32 v39, v39, v69, vcc
	v_cndmask_b32_e32 v38, v38, v68, vcc
	v_cndmask_b32_e32 v37, v37, v71, vcc
	v_cndmask_b32_e32 v36, v36, v70, vcc
	v_cndmask_b32_e32 v35, v35, v51, vcc
	v_cndmask_b32_e32 v34, v34, v50, vcc
	v_cndmask_b32_e32 v33, v33, v49, vcc
	v_cndmask_b32_e32 v32, v32, v48, vcc
	v_pk_mul_f32 v[48:49], v[44:45], s[50:51] op_sel_hi:[1,0]
	v_pk_mul_f32 v[50:51], v[46:47], s[50:51] op_sel_hi:[1,0]
	v_pk_mul_f32 v[52:53], v[40:41], s[50:51] op_sel_hi:[1,0]
	v_pk_mul_f32 v[54:55], v[42:43], s[50:51] op_sel_hi:[1,0]
	v_pk_mul_f32 v[60:61], v[36:37], s[50:51] op_sel_hi:[1,0]
	v_pk_mul_f32 v[62:63], v[38:39], s[50:51] op_sel_hi:[1,0]
	v_pk_mul_f32 v[64:65], v[32:33], s[50:51] op_sel_hi:[1,0]
	v_pk_mul_f32 v[66:67], v[34:35], s[50:51] op_sel_hi:[1,0]
	v_cndmask_b32_e64 v47, v47, v51, s[6:7]
	v_cndmask_b32_e64 v46, v46, v50, s[6:7]
	v_cndmask_b32_e64 v45, v45, v49, s[6:7]
	v_cndmask_b32_e64 v44, v44, v48, s[6:7]
	v_cndmask_b32_e64 v43, v43, v55, s[6:7]
	v_cndmask_b32_e64 v42, v42, v54, s[6:7]
	v_cndmask_b32_e64 v41, v41, v53, s[6:7]
	v_cndmask_b32_e64 v40, v40, v52, s[6:7]
	v_cndmask_b32_e64 v39, v39, v63, s[8:9]
	v_cndmask_b32_e64 v38, v38, v62, s[8:9]
	v_cndmask_b32_e64 v37, v37, v61, s[8:9]
	v_cndmask_b32_e64 v36, v36, v60, s[8:9]
	v_cndmask_b32_e64 v48, v35, v67, s[8:9]
	v_cndmask_b32_e64 v49, v34, v66, s[8:9]
	v_cndmask_b32_e64 v50, v33, v65, s[8:9]
	v_cndmask_b32_e64 v51, v32, v64, s[8:9]
	v_cvt_pk_bf16_f32 v32, v44, v45
	v_cvt_pk_bf16_f32 v33, v46, v47
	v_cvt_pk_bf16_f32 v34, v40, v41
	v_cvt_pk_bf16_f32 v35, v42, v43
	v_cvt_pk_bf16_f32 v36, v36, v37
	v_cvt_pk_bf16_f32 v37, v38, v39
	v_cvt_pk_bf16_f32 v38, v51, v50
	v_cvt_pk_bf16_f32 v39, v49, v48
	global_store_dwordx4 v[56:57], v[32:35], off
	global_store_dwordx4 v[56:57], v[36:39], off offset:256
	global_load_dwordx4 v[32:35], v[58:59], off offset:64
	s_nop 0
	global_load_dwordx4 v[36:39], v[58:59], off
	v_or_b32_e32 v40, s55, v153
	v_cmp_gt_i32_e32 vcc, s81, v40
	v_mad_i64_i32 v[40:41], s[0:1], v40, s90, v[138:139]
	s_and_b64 s[0:1], s[64:65], vcc
	s_and_b64 vcc, s[66:67], vcc
	v_cndmask_b32_e64 v42, v154, v80, s[2:3]
	v_lshl_add_u64 v[40:41], v[40:41], 0, s[70:71]
	v_lshlrev_b32_e32 v136, 7, v42
	v_lshl_add_u64 v[42:43], v[140:141], 0, v[136:137]
	s_waitcnt vmcnt(1)
; __device__ __forceinline__ unsigned pk2(float lo, float hi) { f32x2 v = {lo, hi}; nbf2 r = __builtin_convertvector(v, nbf2); return __builtin_bit_cast(unsigned, r); }
;     __device__ __forceinline__ void operator()(f32x4 (&acc)[2][2][4][2], const pg8::Unit& u, int wr, int wc, int fr, int fq, LAS unsigned char* lds) const {
;     ...
;             for (int m = 0; m < 4; ++m) {
;                 const int r = u.pm * 256 + ai * 128 + wr * 64 + m * 16 + fr;
;                 const bool lat = r < NLAT;
;                 const int t = r & (SEQ - 1);
;                 const int val = (wc & 1) ? (t & 63) : (t >> 6);
;                 const f32x4 cs = *(const f32x4*)(rope + val * 32 + 4 * fq), sn = *(const f32x4*)(rope + val * 32 + 16 + 4 * fq);
;                 bf16_t* rowp = O + (size_t)r * NQKVZ;
; #pragma unroll
;                 for (int bj = 0; bj < 2; ++bj) {
;                     const int cb = u.pn * 256 + bj * 128 + wc * 32;
;                     f32x4 t1 = acc[ai][bj][m][0], t2 = acc[ai][bj][m][1];
;                     if (cb < 1280 && lat) { const f32x4 o1 = t1 * cs - t2 * sn, o2 = t2 * cs + t1 * sn; t1 = o1; t2 = o2; }
;                     if (cb < 1024) { t1 = t1 * qs; t2 = t2 * qs; }
;                     u32x4 w; w.x = pk2(t1[0], t1[1]); w.y = pk2(t1[2], t1[3]); w.z = pk2(t2[0], t2[1]); w.w = pk2(t2[2], t2[3]);
;                     *(u32x4*)(rowp + cb + 8 * fq) = w;
;                 }
	v_pk_mul_f32 v[44:45], v[26:27], v[34:35]
	v_pk_mul_f32 v[46:47], v[24:25], v[32:33]
	v_pk_mul_f32 v[48:49], v[30:31], v[34:35]
	v_pk_mul_f32 v[50:51], v[28:29], v[32:33]
	v_pk_mul_f32 v[52:53], v[18:19], v[34:35]
	v_pk_mul_f32 v[54:55], v[16:17], v[32:33]
	v_pk_mul_f32 v[34:35], v[22:23], v[34:35]
	v_pk_mul_f32 v[32:33], v[20:21], v[32:33]
	s_waitcnt vmcnt(0)
	v_pk_fma_f32 v[44:45], v[30:31], v[38:39], v[44:45] neg_lo:[0,0,1] neg_hi:[0,0,1]
	v_pk_fma_f32 v[46:47], v[28:29], v[36:37], v[46:47] neg_lo:[0,0,1] neg_hi:[0,0,1]
	v_pk_fma_f32 v[48:49], v[26:27], v[38:39], v[48:49]
	v_pk_fma_f32 v[50:51], v[24:25], v[36:37], v[50:51]
	v_pk_fma_f32 v[52:53], v[22:23], v[38:39], v[52:53] neg_lo:[0,0,1] neg_hi:[0,0,1]
	v_pk_fma_f32 v[54:55], v[20:21], v[36:37], v[54:55] neg_lo:[0,0,1] neg_hi:[0,0,1]
	v_pk_fma_f32 v[34:35], v[18:19], v[38:39], v[34:35]
	v_pk_fma_f32 v[32:33], v[16:17], v[36:37], v[32:33]
	v_cndmask_b32_e64 v31, v31, v45, s[0:1]
	v_cndmask_b32_e64 v30, v30, v44, s[0:1]
	v_cndmask_b32_e64 v29, v29, v47, s[0:1]
	v_cndmask_b32_e64 v28, v28, v46, s[0:1]
	v_cndmask_b32_e64 v27, v27, v49, s[0:1]
	v_cndmask_b32_e64 v26, v26, v48, s[0:1]
	v_cndmask_b32_e64 v25, v25, v51, s[0:1]
	v_cndmask_b32_e64 v24, v24, v50, s[0:1]
	v_cndmask_b32_e32 v23, v23, v53, vcc
	v_cndmask_b32_e32 v22, v22, v52, vcc
	v_cndmask_b32_e32 v21, v21, v55, vcc
	v_cndmask_b32_e32 v20, v20, v54, vcc
	v_cndmask_b32_e32 v19, v19, v35, vcc
	v_cndmask_b32_e32 v18, v18, v34, vcc
	v_cndmask_b32_e32 v17, v17, v33, vcc
	v_cndmask_b32_e32 v16, v16, v32, vcc
	v_pk_mul_f32 v[32:33], v[28:29], s[50:51] op_sel_hi:[1,0]
	v_pk_mul_f32 v[34:35], v[30:31], s[50:51] op_sel_hi:[1,0]
	v_pk_mul_f32 v[36:37], v[24:25], s[50:51] op_sel_hi:[1,0]
	v_pk_mul_f32 v[38:39], v[26:27], s[50:51] op_sel_hi:[1,0]
	v_pk_mul_f32 v[44:45], v[20:21], s[50:51] op_sel_hi:[1,0]
	v_pk_mul_f32 v[46:47], v[22:23], s[50:51] op_sel_hi:[1,0]
	v_pk_mul_f32 v[48:49], v[16:17], s[50:51] op_sel_hi:[1,0]
	v_pk_mul_f32 v[50:51], v[18:19], s[50:51] op_sel_hi:[1,0]
	v_cndmask_b32_e64 v31, v31, v35, s[6:7]
	v_cndmask_b32_e64 v30, v30, v34, s[6:7]
	v_cndmask_b32_e64 v29, v29, v33, s[6:7]
	v_cndmask_b32_e64 v28, v28, v32, s[6:7]
	v_cndmask_b32_e64 v27, v27, v39, s[6:7]
	v_cndmask_b32_e64 v26, v26, v38, s[6:7]
	v_cndmask_b32_e64 v25, v25, v37, s[6:7]
	v_cndmask_b32_e64 v24, v24, v36, s[6:7]
	v_cndmask_b32_e64 v23, v23, v47, s[8:9]
	v_cndmask_b32_e64 v22, v22, v46, s[8:9]
	v_cndmask_b32_e64 v21, v21, v45, s[8:9]
	v_cndmask_b32_e64 v20, v20, v44, s[8:9]
	v_cndmask_b32_e64 v32, v19, v51, s[8:9]
	v_cndmask_b32_e64 v33, v18, v50, s[8:9]
	v_cndmask_b32_e64 v34, v17, v49, s[8:9]
	v_cndmask_b32_e64 v35, v16, v48, s[8:9]
	v_cvt_pk_bf16_f32 v16, v28, v29
	v_cvt_pk_bf16_f32 v17, v30, v31
	v_cvt_pk_bf16_f32 v18, v24, v25
	v_cvt_pk_bf16_f32 v19, v26, v27
	v_cvt_pk_bf16_f32 v20, v20, v21
	v_cvt_pk_bf16_f32 v21, v22, v23
	v_cvt_pk_bf16_f32 v22, v35, v34
	v_cvt_pk_bf16_f32 v23, v33, v32
	global_store_dwordx4 v[40:41], v[16:19], off
	global_store_dwordx4 v[40:41], v[20:23], off offset:256
	global_load_dwordx4 v[16:19], v[42:43], off offset:64
	s_nop 0
	global_load_dwordx4 v[20:23], v[42:43], off
	v_or_b32_e32 v24, s55, v154
	s_andn2_b64 vcc, exec, s[4:5]
	v_cmp_gt_i32_e64 s[0:1], s81, v24
	v_mad_i64_i32 v[24:25], s[4:5], v24, s90, v[138:139]
	s_and_b64 s[4:5], s[64:65], s[0:1]
	s_and_b64 s[0:1], s[66:67], s[0:1]
	v_lshl_add_u64 v[24:25], v[24:25], 0, s[70:71]
	s_waitcnt vmcnt(1)
	v_pk_mul_f32 v[26:27], v[10:11], v[18:19]
	v_pk_mul_f32 v[28:29], v[8:9], v[16:17]
	v_pk_mul_f32 v[30:31], v[14:15], v[18:19]
	v_pk_mul_f32 v[32:33], v[12:13], v[16:17]
	v_pk_mul_f32 v[34:35], v[2:3], v[18:19]
	v_pk_mul_f32 v[36:37], v[0:1], v[16:17]
	v_pk_mul_f32 v[18:19], v[6:7], v[18:19]
	v_pk_mul_f32 v[16:17], v[4:5], v[16:17]
	s_waitcnt vmcnt(0)
	v_pk_fma_f32 v[26:27], v[14:15], v[22:23], v[26:27] neg_lo:[0,0,1] neg_hi:[0,0,1]
	v_pk_fma_f32 v[28:29], v[12:13], v[20:21], v[28:29] neg_lo:[0,0,1] neg_hi:[0,0,1]
	v_pk_fma_f32 v[30:31], v[10:11], v[22:23], v[30:31]
	v_pk_fma_f32 v[32:33], v[8:9], v[20:21], v[32:33]
	v_pk_fma_f32 v[34:35], v[6:7], v[22:23], v[34:35] neg_lo:[0,0,1] neg_hi:[0,0,1]
	v_pk_fma_f32 v[36:37], v[4:5], v[20:21], v[36:37] neg_lo:[0,0,1] neg_hi:[0,0,1]
	v_pk_fma_f32 v[18:19], v[2:3], v[22:23], v[18:19]
	v_pk_fma_f32 v[16:17], v[0:1], v[20:21], v[16:17]
	v_cndmask_b32_e64 v15, v15, v27, s[4:5]
	v_cndmask_b32_e64 v14, v14, v26, s[4:5]
	v_cndmask_b32_e64 v13, v13, v29, s[4:5]
	v_cndmask_b32_e64 v12, v12, v28, s[4:5]
	v_cndmask_b32_e64 v11, v11, v31, s[4:5]
	v_cndmask_b32_e64 v10, v10, v30, s[4:5]
	v_cndmask_b32_e64 v9, v9, v33, s[4:5]
	v_cndmask_b32_e64 v8, v8, v32, s[4:5]
	v_cndmask_b32_e64 v7, v7, v35, s[0:1]
	v_cndmask_b32_e64 v6, v6, v34, s[0:1]
	v_cndmask_b32_e64 v5, v5, v37, s[0:1]
	v_cndmask_b32_e64 v4, v4, v36, s[0:1]
	v_cndmask_b32_e64 v3, v3, v19, s[0:1]
	v_cndmask_b32_e64 v2, v2, v18, s[0:1]
	v_cndmask_b32_e64 v1, v1, v17, s[0:1]
	v_cndmask_b32_e64 v0, v0, v16, s[0:1]
	v_pk_mul_f32 v[16:17], v[12:13], s[50:51] op_sel_hi:[1,0]
	v_pk_mul_f32 v[18:19], v[14:15], s[50:51] op_sel_hi:[1,0]
	v_pk_mul_f32 v[20:21], v[8:9], s[50:51] op_sel_hi:[1,0]
	v_pk_mul_f32 v[22:23], v[10:11], s[50:51] op_sel_hi:[1,0]
	v_pk_mul_f32 v[26:27], v[4:5], s[50:51] op_sel_hi:[1,0]
	v_pk_mul_f32 v[28:29], v[6:7], s[50:51] op_sel_hi:[1,0]
	v_pk_mul_f32 v[30:31], v[0:1], s[50:51] op_sel_hi:[1,0]
	v_pk_mul_f32 v[32:33], v[2:3], s[50:51] op_sel_hi:[1,0]
	v_cndmask_b32_e64 v15, v15, v19, s[6:7]
	v_cndmask_b32_e64 v14, v14, v18, s[6:7]
	v_cndmask_b32_e64 v13, v13, v17, s[6:7]
	v_cndmask_b32_e64 v12, v12, v16, s[6:7]
	v_cndmask_b32_e64 v11, v11, v23, s[6:7]
	v_cndmask_b32_e64 v10, v10, v22, s[6:7]
	v_cndmask_b32_e64 v9, v9, v21, s[6:7]
	v_cndmask_b32_e64 v8, v8, v20, s[6:7]
	v_cndmask_b32_e64 v7, v7, v29, s[8:9]
	v_cndmask_b32_e64 v6, v6, v28, s[8:9]
	v_cndmask_b32_e64 v5, v5, v27, s[8:9]
	v_cndmask_b32_e64 v4, v4, v26, s[8:9]
	v_cndmask_b32_e64 v16, v3, v33, s[8:9]
	v_cndmask_b32_e64 v17, v2, v32, s[8:9]
	v_cndmask_b32_e64 v18, v1, v31, s[8:9]
	v_cndmask_b32_e64 v19, v0, v30, s[8:9]
	v_cvt_pk_bf16_f32 v0, v12, v13
	v_cvt_pk_bf16_f32 v1, v14, v15
	v_cvt_pk_bf16_f32 v2, v8, v9
	v_cvt_pk_bf16_f32 v3, v10, v11
	s_mov_b64 s[0:1], -1
	v_cvt_pk_bf16_f32 v4, v4, v5
	v_cvt_pk_bf16_f32 v5, v6, v7
	v_cvt_pk_bf16_f32 v6, v19, v18
	v_cvt_pk_bf16_f32 v7, v17, v16
	global_store_dwordx4 v[24:25], v[0:3], off
	global_store_dwordx4 v[24:25], v[4:7], off offset:256
	s_cbranch_vccnz .LBB0_181
	s_andn2_b64 vcc, exec, s[42:43]
	s_cbranch_vccnz .LBB0_180
	s_barrier
	s_branch .LBB0_180
; __device__ __forceinline__ unsigned pk2(float lo, float hi) { f32x2 v = {lo, hi}; nbf2 r = __builtin_convertvector(v, nbf2); return __builtin_bit_cast(unsigned, r); }
;     __device__ __forceinline__ void operator()(f32x4 (&acc)[2][2][4][2], const pg8::Unit& u, int wr, int wc, int fr, int fq, LAS unsigned char* lds) const {
;     ...
;                 bf16_t* rowp = O + (size_t)r * NQKVZ;
; #pragma unroll
;                 for (int bj = 0; bj < 2; ++bj) {
;                     const int cb = u.pn * 256 + bj * 128 + wc * 32;
;                     f32x4 t1 = acc[ai][bj][m][0], t2 = acc[ai][bj][m][1];
;                     if (cb < 1280 && lat) { const f32x4 o1 = t1 * cs - t2 * sn, o2 = t2 * cs + t1 * sn; t1 = o1; t2 = o2; }
;                     if (cb < 1024) { t1 = t1 * qs; t2 = t2 * qs; }
;                     u32x4 w; w.x = pk2(t1[0], t1[1]); w.y = pk2(t1[2], t1[3]); w.z = pk2(t2[0], t2[1]); w.w = pk2(t2[2], t2[3]);
;                     *(u32x4*)(rowp + cb + 8 * fq) = w;
;                 }
.Lqkvz_plain:
	s_lshl_b32 s55, s0, 8
	s_add_i32 s55, s55, s82
	s_bfe_u32 s0, s55, 0x60006
	v_mov_b32_e32 v158, s0
	v_cndmask_b32_e64 v136, v150, v158, s[2:3]
	v_lshlrev_b32_e32 v136, 7, v136
	v_lshl_add_u64 v[164:165], v[140:141], 0, v[136:137]
	s_lshl_b32 s0, s1, 8
	s_or_b32 s8, s0, s83
	v_or_b32_e32 v136, s55, v150
	s_cmpk_lt_i32 s8, 0x500
	v_cmp_gt_i32_e32 vcc, s81, v136
	v_mad_i64_i32 v[168:169], s[0:1], v136, s90, v[138:139]
	s_cselect_b64 s[64:65], -1, 0
	s_and_b64 s[0:1], s[64:65], vcc
	s_cmpk_lt_i32 s8, 0x400
	s_cselect_b64 s[6:7], -1, 0
	s_ashr_i32 s9, s8, 31
	s_lshl_b64 s[70:71], s[8:9], 1
	v_cndmask_b32_e64 v136, v152, v158, s[2:3]
	v_lshlrev_b32_e32 v136, 7, v136
	v_lshl_add_u64 v[170:171], v[140:141], 0, v[136:137]
	s_or_b32 s0, s8, 0x80
	s_cmpk_lt_i32 s0, 0x500
	s_cselect_b64 s[66:67], -1, 0
	v_mov_b32_e32 v136, v122
	v_mov_b32_e32 v122, v121
	v_mov_b32_e32 v159, v120
	s_and_b64 vcc, s[66:67], vcc
	v_cvt_pk_bf16_f32 v120, v124, v125
	v_cvt_pk_bf16_f32 v121, v126, v127
	v_cvt_pk_bf16_f32 v122, v159, v122
	v_cvt_pk_bf16_f32 v123, v136, v123
	v_lshl_add_u64 v[124:125], v[168:169], 0, s[70:71]
	s_cmpk_lt_i32 s0, 0x400
	global_store_dwordx4 v[124:125], v[120:123], off
	s_nop 1
	s_cselect_b64 s[8:9], -1, 0
	v_mov_b32_e32 v120, v114
	v_mov_b32_e32 v114, v113
	v_mov_b32_e32 v121, v112
	v_cvt_pk_bf16_f32 v112, v116, v117
	v_cvt_pk_bf16_f32 v113, v118, v119
	v_cvt_pk_bf16_f32 v114, v121, v114
	v_cvt_pk_bf16_f32 v115, v120, v115
	global_store_dwordx4 v[124:125], v[112:115], off offset:256
	s_nop 1
	v_or_b32_e32 v120, s55, v152
	v_cmp_gt_i32_e32 vcc, s81, v120
	v_mad_i64_i32 v[120:121], s[0:1], v120, s90, v[138:139]
	s_and_b64 s[0:1], s[64:65], vcc
	s_and_b64 vcc, s[66:67], vcc
	v_cndmask_b32_e64 v122, v153, v158, s[2:3]
	v_lshlrev_b32_e32 v136, 7, v122
	v_lshl_add_u64 v[120:121], v[120:121], 0, s[70:71]
	v_lshl_add_u64 v[122:123], v[140:141], 0, v[136:137]
	v_mov_b32_e32 v112, v99
	v_mov_b32_e32 v113, v98
	v_mov_b32_e32 v114, v97
	v_mov_b32_e32 v115, v96
	v_cvt_pk_bf16_f32 v96, v108, v109
	v_cvt_pk_bf16_f32 v97, v110, v111
	v_cvt_pk_bf16_f32 v98, v104, v105
	v_cvt_pk_bf16_f32 v99, v106, v107
	v_cvt_pk_bf16_f32 v100, v100, v101
	v_cvt_pk_bf16_f32 v101, v102, v103
	v_cvt_pk_bf16_f32 v102, v115, v114
	v_cvt_pk_bf16_f32 v103, v113, v112
	global_store_dwordx4 v[120:121], v[96:99], off
	s_nop 1
	global_store_dwordx4 v[120:121], v[100:103], off offset:256
	s_nop 1
	v_or_b32_e32 v104, s55, v153
	v_cmp_gt_i32_e32 vcc, s81, v104
	v_mad_i64_i32 v[104:105], s[0:1], v104, s90, v[138:139]
	s_and_b64 s[0:1], s[64:65], vcc
	s_and_b64 vcc, s[66:67], vcc
	v_cndmask_b32_e64 v106, v154, v158, s[2:3]
	v_lshlrev_b32_e32 v136, 7, v106
	v_lshl_add_u64 v[104:105], v[104:105], 0, s[70:71]
	v_lshl_add_u64 v[106:107], v[140:141], 0, v[136:137]
	v_mov_b32_e32 v96, v83
	v_mov_b32_e32 v97, v82
	v_mov_b32_e32 v98, v81
	v_mov_b32_e32 v99, v80
	v_cvt_pk_bf16_f32 v80, v92, v93
	v_cvt_pk_bf16_f32 v81, v94, v95
	v_cvt_pk_bf16_f32 v82, v88, v89
	v_cvt_pk_bf16_f32 v83, v90, v91
	v_cvt_pk_bf16_f32 v84, v84, v85
	v_cvt_pk_bf16_f32 v85, v86, v87
	v_cvt_pk_bf16_f32 v86, v99, v98
	v_cvt_pk_bf16_f32 v87, v97, v96
	global_store_dwordx4 v[104:105], v[80:83], off
	s_nop 1
	global_store_dwordx4 v[104:105], v[84:87], off offset:256
	s_nop 1
	v_or_b32_e32 v80, s55, v154
	v_cmp_gt_i32_e32 vcc, s81, v80
	v_mad_i64_i32 v[80:81], s[0:1], v80, s90, v[138:139]
	s_addk_i32 s55, 0x80
	s_bfe_u32 s0, s55, 0x60006
	v_lshl_add_u64 v[90:91], v[80:81], 0, s[70:71]
	v_mov_b32_e32 v80, s0
	s_and_b64 s[0:1], s[64:65], vcc
	s_and_b64 vcc, s[66:67], vcc
	v_cndmask_b32_e64 v81, v150, v80, s[2:3]
	v_lshlrev_b32_e32 v136, 7, v81
	v_lshl_add_u64 v[92:93], v[140:141], 0, v[136:137]
	v_mov_b32_e32 v81, v67
	v_mov_b32_e32 v82, v66
	v_mov_b32_e32 v83, v65
; __device__ __forceinline__ unsigned pk2(float lo, float hi) { f32x2 v = {lo, hi}; nbf2 r = __builtin_convertvector(v, nbf2); return __builtin_bit_cast(unsigned, r); }
;     __device__ __forceinline__ void operator()(f32x4 (&acc)[2][2][4][2], const pg8::Unit& u, int wr, int wc, int fr, int fq, LAS unsigned char* lds) const {
;     ...
;                 bf16_t* rowp = O + (size_t)r * NQKVZ;
; #pragma unroll
;                 for (int bj = 0; bj < 2; ++bj) {
;                     const int cb = u.pn * 256 + bj * 128 + wc * 32;
;                     f32x4 t1 = acc[ai][bj][m][0], t2 = acc[ai][bj][m][1];
;                     if (cb < 1280 && lat) { const f32x4 o1 = t1 * cs - t2 * sn, o2 = t2 * cs + t1 * sn; t1 = o1; t2 = o2; }
;                     if (cb < 1024) { t1 = t1 * qs; t2 = t2 * qs; }
;                     u32x4 w; w.x = pk2(t1[0], t1[1]); w.y = pk2(t1[2], t1[3]); w.z = pk2(t2[0], t2[1]); w.w = pk2(t2[2], t2[3]);
;                     *(u32x4*)(rowp + cb + 8 * fq) = w;
;                 }
	v_mov_b32_e32 v84, v64
	v_cvt_pk_bf16_f32 v64, v76, v77
	v_cvt_pk_bf16_f32 v65, v78, v79
	v_cvt_pk_bf16_f32 v66, v72, v73
	v_cvt_pk_bf16_f32 v67, v74, v75
	v_cvt_pk_bf16_f32 v68, v68, v69
	v_cvt_pk_bf16_f32 v69, v70, v71
	v_cvt_pk_bf16_f32 v70, v84, v83
	v_cvt_pk_bf16_f32 v71, v82, v81
	global_store_dwordx4 v[90:91], v[64:67], off
	s_nop 1
	global_store_dwordx4 v[90:91], v[68:71], off offset:256
	s_nop 1
	v_or_b32_e32 v72, s55, v150
	v_cmp_gt_i32_e32 vcc, s81, v72
	v_mad_i64_i32 v[72:73], s[0:1], v72, s90, v[138:139]
	s_and_b64 s[0:1], s[64:65], vcc
	s_and_b64 vcc, s[66:67], vcc
	v_cndmask_b32_e64 v74, v152, v80, s[2:3]
	v_lshl_add_u64 v[72:73], v[72:73], 0, s[70:71]
	v_lshlrev_b32_e32 v136, 7, v74
	v_lshl_add_u64 v[74:75], v[140:141], 0, v[136:137]
	v_mov_b32_e32 v64, v51
	v_mov_b32_e32 v65, v50
	v_mov_b32_e32 v66, v49
	v_mov_b32_e32 v67, v48
	v_cvt_pk_bf16_f32 v48, v60, v61
	v_cvt_pk_bf16_f32 v49, v62, v63
	v_cvt_pk_bf16_f32 v50, v56, v57
	v_cvt_pk_bf16_f32 v51, v58, v59
	v_cvt_pk_bf16_f32 v52, v52, v53
	v_cvt_pk_bf16_f32 v53, v54, v55
	v_cvt_pk_bf16_f32 v54, v67, v66
	v_cvt_pk_bf16_f32 v55, v65, v64
	global_store_dwordx4 v[72:73], v[48:51], off
	s_nop 1
	global_store_dwordx4 v[72:73], v[52:55], off offset:256
	s_nop 1
	v_or_b32_e32 v56, s55, v152
	v_cmp_gt_i32_e32 vcc, s81, v56
	v_mad_i64_i32 v[56:57], s[0:1], v56, s90, v[138:139]
	s_and_b64 s[0:1], s[64:65], vcc
	s_and_b64 vcc, s[66:67], vcc
	v_cndmask_b32_e64 v58, v153, v80, s[2:3]
	v_lshl_add_u64 v[56:57], v[56:57], 0, s[70:71]
	v_lshlrev_b32_e32 v136, 7, v58
	v_lshl_add_u64 v[58:59], v[140:141], 0, v[136:137]
	v_mov_b32_e32 v48, v35
	v_mov_b32_e32 v49, v34
	v_mov_b32_e32 v50, v33
	v_mov_b32_e32 v51, v32
	v_cvt_pk_bf16_f32 v32, v44, v45
	v_cvt_pk_bf16_f32 v33, v46, v47
	v_cvt_pk_bf16_f32 v34, v40, v41
	v_cvt_pk_bf16_f32 v35, v42, v43
	v_cvt_pk_bf16_f32 v36, v36, v37
	v_cvt_pk_bf16_f32 v37, v38, v39
	v_cvt_pk_bf16_f32 v38, v51, v50
	v_cvt_pk_bf16_f32 v39, v49, v48
	global_store_dwordx4 v[56:57], v[32:35], off
	s_nop 1
	global_store_dwordx4 v[56:57], v[36:39], off offset:256
	s_nop 1
	v_or_b32_e32 v40, s55, v153
	v_cmp_gt_i32_e32 vcc, s81, v40
	v_mad_i64_i32 v[40:41], s[0:1], v40, s90, v[138:139]
	s_and_b64 s[0:1], s[64:65], vcc
	s_and_b64 vcc, s[66:67], vcc
	v_cndmask_b32_e64 v42, v154, v80, s[2:3]
	v_lshl_add_u64 v[40:41], v[40:41], 0, s[70:71]
	v_lshlrev_b32_e32 v136, 7, v42
	v_lshl_add_u64 v[42:43], v[140:141], 0, v[136:137]
	v_mov_b32_e32 v32, v19
	v_mov_b32_e32 v33, v18
	v_mov_b32_e32 v34, v17
	v_mov_b32_e32 v35, v16
	v_cvt_pk_bf16_f32 v16, v28, v29
	v_cvt_pk_bf16_f32 v17, v30, v31
	v_cvt_pk_bf16_f32 v18, v24, v25
	v_cvt_pk_bf16_f32 v19, v26, v27
	v_cvt_pk_bf16_f32 v20, v20, v21
	v_cvt_pk_bf16_f32 v21, v22, v23
	v_cvt_pk_bf16_f32 v22, v35, v34
	v_cvt_pk_bf16_f32 v23, v33, v32
	global_store_dwordx4 v[40:41], v[16:19], off
	s_nop 1
	global_store_dwordx4 v[40:41], v[20:23], off offset:256
	s_nop 1
	v_or_b32_e32 v24, s55, v154
	s_andn2_b64 vcc, exec, s[4:5]
	v_cmp_gt_i32_e64 s[0:1], s81, v24
	v_mad_i64_i32 v[24:25], s[4:5], v24, s90, v[138:139]
	s_and_b64 s[4:5], s[64:65], s[0:1]
	s_and_b64 s[0:1], s[66:67], s[0:1]
	v_lshl_add_u64 v[24:25], v[24:25], 0, s[70:71]
	v_mov_b32_e32 v16, v3
	v_mov_b32_e32 v17, v2
	v_mov_b32_e32 v18, v1
	v_mov_b32_e32 v19, v0
	v_cvt_pk_bf16_f32 v0, v12, v13
	v_cvt_pk_bf16_f32 v1, v14, v15
	v_cvt_pk_bf16_f32 v2, v8, v9
	v_cvt_pk_bf16_f32 v3, v10, v11
	s_mov_b64 s[0:1], -1
	v_cvt_pk_bf16_f32 v4, v4, v5
	v_cvt_pk_bf16_f32 v5, v6, v7
	v_cvt_pk_bf16_f32 v6, v19, v18
	v_cvt_pk_bf16_f32 v7, v17, v16
	global_store_dwordx4 v[24:25], v[0:3], off
	s_nop 1
	global_store_dwordx4 v[24:25], v[4:7], off offset:256
	s_nop 1
	s_cbranch_vccnz .LBB0_181
	s_andn2_b64 vcc, exec, s[42:43]
	s_cbranch_vccnz .LBB0_180
	s_barrier
	s_branch .LBB0_180
